# speedup vs baseline: 1.0076x; 1.0076x over previous
; __device__ void phase_prep(const Params& p, char* smem) {
;     ...
;   if (bid == 0 && tid < 64) p.qctr[tid * 16] = 0;
.LBB0_81:
	s_or_b64 exec, exec, s[4:5]
	v_readlane_b32 s0, v252, 0
	v_readlane_b32 s1, v252, 1
	s_cmp_eq_u32 s0, 0
	s_cselect_b64 s[0:1], -1, 0
	v_cmp_gt_u32_e32 vcc, 64, v66
	s_and_b64 s[0:1], s[0:1], vcc
	s_and_saveexec_b64 s[4:5], s[0:1]
	s_cbranch_execz .LBB0_83
	v_lshlrev_b32_e32 v1, 6, v66
	v_mov_b32_e32 v2, 0
	global_atomic_swap v1, v2, s[90:91]

; __global__ void __launch_bounds__(NTHR) mega(Params p) {
;     ...
;   if (ph < 0) cg::this_grid().sync();
.LBB0_170:
	v_cndmask_b32_e64 v1, 0, 1, s[10:11]
	v_cmp_ne_u32_e64 s[0:1], 1, v1
	s_andn2_b64 vcc, exec, s[10:11]
	s_nop 0
	v_writelane_b32 v252, s0, 38
	s_nop 1
	v_writelane_b32 v252, s1, 39
	s_cbranch_vccnz .LBB0_182
	v_and_b32_e32 v1, 0x3fffffff, v0
	v_cmp_eq_u32_e32 vcc, 0, v1
	s_waitcnt vmcnt(0) lgkmcnt(0)
	s_barrier
	s_and_saveexec_b64 s[6:7], vcc
	s_cbranch_execz .LBB0_181
	v_readlane_b32 s0, v252, 34
	v_readlane_b32 s1, v252, 35
	buffer_wbl2 sc1
	s_waitcnt vmcnt(0)
	s_load_dword s8, s[0:1], 0x130
	v_mov_b32_e32 v1, 0
	v_mov_b32_e32 v2, 1
	global_atomic_add v1, v2, s[90:91] offset:1152
	s_mov_b32 s9, 0x40000
	s_waitcnt lgkmcnt(0)
.Lxb2_poll:
	global_load_dword v3, v1, s[90:91] offset:1152 sc1
	s_waitcnt vmcnt(0)
	v_readfirstlane_b32 s2, v3
	s_cmp_ge_u32 s2, s8
	s_cbranch_scc1 .Lxb2_go
	s_sleep 2
	s_sub_u32 s9, s9, 1
	s_cmp_lg_u32 s9, 0
	s_cbranch_scc1 .Lxb2_poll
.Lxb2_go:
	buffer_inv sc1
	s_waitcnt vmcnt(0)

; __global__ void __launch_bounds__(NTHR) mega(Params p) {
;     ...
;   if (ph < 0) cg::this_grid().sync();
.LBB0_225:
	v_readlane_b32 s0, v252, 38
	v_readlane_b32 s1, v252, 39
	s_and_b64 vcc, exec, s[0:1]
	s_cbranch_vccnz .LBB0_237
	v_and_b32_e32 v1, 0x3fffffff, v0
	v_cmp_eq_u32_e32 vcc, 0, v1
	s_waitcnt vmcnt(0) lgkmcnt(0)
	s_barrier
	s_and_saveexec_b64 s[6:7], vcc
	s_cbranch_execz .LBB0_236
	v_readlane_b32 s0, v252, 34
	v_readlane_b32 s1, v252, 35
	buffer_wbl2 sc1
	s_waitcnt vmcnt(0)
	s_load_dword s8, s[0:1], 0x130
	v_mov_b32_e32 v1, 0
	v_mov_b32_e32 v2, 1
	global_atomic_add v1, v2, s[90:91] offset:1280
	s_mov_b32 s9, 0x40000
	s_waitcnt lgkmcnt(0)
.Lxb3_poll:
	global_load_dword v3, v1, s[90:91] offset:1280 sc1
	s_waitcnt vmcnt(0)
	v_readfirstlane_b32 s2, v3
	s_cmp_ge_u32 s2, s8
	s_cbranch_scc1 .Lxb3_go
	s_sleep 2
	s_sub_u32 s9, s9, 1
	s_cmp_lg_u32 s9, 0
	s_cbranch_scc1 .Lxb3_poll

; __global__ void __launch_bounds__(NTHR) mega(Params p) {
;     ...
;   if (ph < 0) cg::this_grid().sync();
.LBB0_364:
	v_readlane_b32 s0, v252, 38
	v_readlane_b32 s1, v252, 39
	s_and_b64 vcc, exec, s[0:1]
	s_cbranch_vccnz .LBB0_376
	v_and_b32_e32 v1, 0x3fffffff, v0
	v_cmp_eq_u32_e32 vcc, 0, v1
	s_waitcnt vmcnt(0) lgkmcnt(0)
	s_barrier
	s_and_saveexec_b64 s[6:7], vcc
	s_cbranch_execz .LBB0_375
	v_readlane_b32 s0, v252, 34
	v_readlane_b32 s1, v252, 35
	buffer_wbl2 sc1
	s_waitcnt vmcnt(0)
	s_load_dword s8, s[0:1], 0x130
	v_mov_b32_e32 v1, 0
	v_mov_b32_e32 v2, 1
	global_atomic_add v1, v2, s[90:91] offset:1408
	s_mov_b32 s9, 0x40000
	s_waitcnt lgkmcnt(0)
.Lxb4_poll:
	global_load_dword v3, v1, s[90:91] offset:1408 sc1
	s_waitcnt vmcnt(0)
	v_readfirstlane_b32 s2, v3
	s_cmp_ge_u32 s2, s8
	s_cbranch_scc1 .Lxb4_go
	s_sleep 2
	s_sub_u32 s9, s9, 1
	s_cmp_lg_u32 s9, 0
	s_cbranch_scc1 .Lxb4_poll

; __global__ void __launch_bounds__(NTHR) mega(Params p) {
;     ...
;   if (ph < 0) cg::this_grid().sync();
.LBB0_438:
	v_readlane_b32 s0, v252, 38
	v_readlane_b32 s1, v252, 39
	s_and_b64 vcc, exec, s[0:1]
	s_cbranch_vccnz .LBB0_450
	v_and_b32_e32 v1, 0x3fffffff, v0
	v_cmp_eq_u32_e32 vcc, 0, v1
	s_waitcnt vmcnt(0) lgkmcnt(0)
	s_barrier
	s_and_saveexec_b64 s[4:5], vcc
	s_cbranch_execz .LBB0_449
	v_readlane_b32 s0, v252, 34
	v_readlane_b32 s1, v252, 35
	buffer_wbl2 sc1
	s_waitcnt vmcnt(0)
	s_load_dword s8, s[0:1], 0x130
	v_mov_b32_e32 v1, 0
	v_mov_b32_e32 v2, 1
	global_atomic_add v1, v2, s[90:91] offset:1536
	s_mov_b32 s9, 0x40000
	s_waitcnt lgkmcnt(0)
.Lxb5_poll:
	global_load_dword v3, v1, s[90:91] offset:1536 sc1
	s_waitcnt vmcnt(0)
	v_readfirstlane_b32 s2, v3
	s_cmp_ge_u32 s2, s8
	s_cbranch_scc1 .Lxb5_go
	s_sleep 2
	s_sub_u32 s9, s9, 1
	s_cmp_lg_u32 s9, 0
	s_cbranch_scc1 .Lxb5_poll
